# LN1 router: bias loaded once per phase (no per-tile global load + vmcnt(0)), wave-local LG barrier removed, router MFMA LDS operand reads double-buffered
# baseline (speedup 1.0000x reference)
; #define LAS __attribute__((address_space(3)))
; __device__ __forceinline__ void ln1_router_phase(const Args& a, int l, LAS unsigned char* lds, const int tid, const int rpt) {
;     const int lane = tid & 63, wave = __builtin_amdgcn_readfirstlane(tid >> 6);
;     unsigned char* ws = a.ws;
;     const bf16_t* ypre = (const bf16_t*)(ws + WS_YPRE); bf16_t* x1b = (bf16_t*)(ws + WS_X1B); unsigned char* x1q = ws + WS_X1Q;
;     const float* g1 = a.in[8] + l * 1024; const float* b1 = a.in[9] + l * 1024; const float* rw = a.in[10] + (size_t)l * 1024 * 32; const float* rb = a.in[11] + l * 32;
;     int* cnt = (int*)(ws + WS_CTL) + l * 32; int* slot_e = (int*)(ws + WS_SLOTE); int* slot_pos = (int*)(ws + WS_SLOTPOS); float* slot_g = (float*)(ws + WS_SLOTG);
;     LAS float* X = (LAS float*)lds; LAS float* PART = X + 16 * 1028; LAS float* LG = PART + 8 * 512;
;     LAS int* LCNT = (LAS int*)(LG + 512); LAS int* LBASE = LCNT + 32; LAS int* LSLOT = LBASE + 32; constexpr int MAXLOC = 16; LAS float* TV = (LAS float*)(LSLOT + MAXLOC * 64);
;     if (tid < 32) LCNT[tid] = 0;
;     __syncthreads();
.LBB0_117:
	v_readlane_b32 s0, v254, 48
	s_cmp_gt_i32 s0, 4
	s_mov_b64 s[0:1], -1
	s_cbranch_scc0 .LBB0_148
	v_readfirstlane_b32 s15, v168
	v_cmp_gt_i32_e64 s[36:37], 32, v168
	s_and_saveexec_b64 s[0:1], s[36:37]
	v_lshl_add_u32 v0, v168, 2, 0
	v_add_u32_e32 v0, 0x14900, v0
	ds_write_b32 v0, v33
	s_or_b64 exec, exec, s[0:1]
	v_readlane_b32 s0, v251, 50
	v_readlane_b32 s1, v251, 51
	s_andn2_b64 vcc, exec, s[0:1]
	s_mov_b32 s12, 0
	s_waitcnt vmcnt(0) lgkmcnt(0)
	s_barrier
	s_cbranch_vccnz .LBB0_135
; __device__ __forceinline__ void ln1_router_phase(const Args& a, int l, LAS unsigned char* lds, const int tid, const int rpt) {
;     ...
;     f32x4 gv[4], bv[4];
; #pragma unroll
;     for (int j = 0; j < 4; ++j) { gv[j] = *(const f32x4*)(g1 + 4 * (64 * j + lane)); bv[j] = *(const f32x4*)(b1 + 4 * (64 * j + lane)); }
;     const int r16 = lane & 15, kq = lane >> 4, kb = wave * 128;
;     float w0[32], w1[32];
; #pragma unroll
;     for (int ks = 0; ks < 32; ++ks) { const int k = kb + 4 * ks + kq; w0[ks] = rw[k * 32 + r16]; w1[ks] = rw[k * 32 + 16 + r16]; }
;     u32x2 pre[2][4];
;     { const int t0 = blockIdx.x;
;       if (t0 < NTOK / 16) {
; #pragma unroll
;         for (int rr = 0; rr < 2; ++rr)
; #pragma unroll
;             for (int j = 0; j < 4; ++j) pre[rr][j] = *(const u32x2*)(ypre + (size_t)(t0 * 16 + 2 * wave + rr) * 1024 + 4 * (64 * j + lane)); } }
;     ...
;         { float s = rb[tid & 31];
	v_readlane_b32 s0, v254, 59
	v_readlane_b32 s16, v254, 61
	s_ashr_i32 s12, s15, 6
	v_lshlrev_b32_e32 v39, 4, v248
	v_readlane_b32 s1, v254, 60
	v_readlane_b32 s17, v254, 62
	v_lshrrev_b32_e32 v45, 4, v248
	s_nop 2
	global_load_dwordx4 v[0:3], v39, s[0:1]
	global_load_dwordx4 v[4:7], v39, s[0:1] offset:1024
	global_load_dwordx4 v[8:11], v39, s[16:17]
	global_load_dwordx4 v[12:15], v39, s[16:17] offset:1024
	global_load_dwordx4 v[16:19], v39, s[0:1] offset:2048
	global_load_dwordx4 v[20:23], v39, s[0:1] offset:3072
	global_load_dwordx4 v[24:27], v39, s[16:17] offset:2048
	global_load_dwordx4 v[28:31], v39, s[16:17] offset:3072
	v_and_b32_e32 v44, 15, v168
	v_lshlrev_b32_e32 v32, 5, v45
	s_lshl_b32 s0, s12, 12
	v_or3_b32 v34, s0, v32, v44
	v_readlane_b32 s0, v254, 63
	v_ashrrev_i32_e32 v35, 31, v34
	v_readlane_b32 s1, v249, 0
	s_lshl_b32 s15, s12, 1
	v_readlane_b32 s20, v251, 46
	v_lshl_add_u64 v[34:35], v[34:35], 2, s[0:1]
	s_movk_i32 s0, 0x1000
	v_add_co_u32_e32 v36, vcc, s0, v34
	s_movk_i32 s0, 0x2000
	s_nop 0
	v_addc_co_u32_e32 v37, vcc, 0, v35, vcc
	v_add_co_u32_e32 v40, vcc, s0, v34
	global_load_dword v76, v[34:35], off
	global_load_dword v77, v[34:35], off offset:64
	global_load_dword v78, v[34:35], off offset:512
	global_load_dword v79, v[34:35], off offset:576
	global_load_dword v80, v[34:35], off offset:1024
	global_load_dword v81, v[34:35], off offset:1088
	global_load_dword v82, v[34:35], off offset:1536
	global_load_dword v83, v[34:35], off offset:1600
	global_load_dword v84, v[34:35], off offset:2048
	global_load_dword v85, v[34:35], off offset:2112
	global_load_dword v86, v[34:35], off offset:2560
	global_load_dword v87, v[34:35], off offset:2624
	global_load_dword v88, v[34:35], off offset:3072
	global_load_dword v89, v[34:35], off offset:3136
	global_load_dword v90, v[34:35], off offset:3584
	global_load_dword v91, v[34:35], off offset:3648
	v_addc_co_u32_e32 v41, vcc, 0, v35, vcc
	global_load_dword v92, v[36:37], off offset:64
	global_load_dword v93, v[36:37], off offset:512
	global_load_dword v94, v[36:37], off offset:576
	global_load_dword v95, v[36:37], off offset:1024
	global_load_dword v96, v[36:37], off offset:1088
	global_load_dword v97, v[36:37], off offset:1536
	global_load_dword v98, v[36:37], off offset:1600
	global_load_dword v99, v[36:37], off offset:2048
	global_load_dword v100, v[40:41], off offset:-4096
	global_load_dword v101, v[40:41], off
	global_load_dword v102, v[40:41], off offset:64
	global_load_dword v103, v[40:41], off offset:512
	global_load_dword v104, v[40:41], off offset:576
	global_load_dword v105, v[40:41], off offset:1024
	global_load_dword v106, v[40:41], off offset:1088
	global_load_dword v107, v[40:41], off offset:1536
	global_load_dword v108, v[40:41], off offset:1600
	global_load_dword v109, v[40:41], off offset:2048
	global_load_dword v110, v[40:41], off offset:2112
	global_load_dword v111, v[40:41], off offset:2560
	global_load_dword v112, v[40:41], off offset:2624
	global_load_dword v113, v[40:41], off offset:3072
	global_load_dword v114, v[40:41], off offset:3136
	global_load_dword v115, v[40:41], off offset:3584
	global_load_dword v116, v[40:41], off offset:3648
	s_movk_i32 s0, 0x3000
	v_add_co_u32_e32 v34, vcc, s0, v34
	v_readlane_b32 s0, v251, 52
	s_nop 0
	v_addc_co_u32_e32 v35, vcc, 0, v35, vcc
	global_load_dword v117, v[36:37], off offset:2112
	global_load_dword v118, v[36:37], off offset:2560
	global_load_dword v119, v[36:37], off offset:2624
	global_load_dword v120, v[36:37], off offset:3072
	global_load_dword v121, v[36:37], off offset:3136
	global_load_dword v122, v[36:37], off offset:3584
	global_load_dword v123, v[36:37], off offset:3648
	global_load_dword v124, v[34:35], off
	global_load_dword v125, v[34:35], off offset:64
	global_load_dword v126, v[34:35], off offset:512
	global_load_dword v127, v[34:35], off offset:576
	global_load_dword v128, v[34:35], off offset:1024
	global_load_dword v129, v[34:35], off offset:1088
	global_load_dword v130, v[34:35], off offset:1536
	global_load_dword v131, v[34:35], off offset:1600
	global_load_dword v132, v[34:35], off offset:2048
	global_load_dword v133, v[34:35], off offset:2112
	global_load_dword v134, v[34:35], off offset:2560
	global_load_dword v135, v[34:35], off offset:2624
	global_load_dword v136, v[34:35], off offset:3072
	global_load_dword v137, v[34:35], off offset:3136
	global_load_dword v138, v[34:35], off offset:3584
	global_load_dword v139, v[34:35], off offset:3648
	s_add_i32 s0, s15, s0
	s_ashr_i32 s1, s0, 31
	s_lshl_b64 s[16:17], s[0:1], 11
	v_readlane_b32 s21, v251, 47
	s_add_u32 s16, s20, s16
	s_addc_u32 s17, s21, s17
	s_or_b32 s0, s0, 1
	s_ashr_i32 s1, s0, 31
	s_lshl_b64 s[0:1], s[0:1], 11
	s_add_u32 s0, s20, s0
	v_lshlrev_b32_e32 v62, 3, v248
	s_addc_u32 s1, s21, s1
	global_load_dwordx2 v[34:35], v62, s[16:17]
	global_load_dwordx2 v[36:37], v62, s[16:17] offset:512
	global_load_dwordx2 v[40:41], v62, s[16:17] offset:1024
	global_load_dwordx2 v[42:43], v62, s[16:17] offset:1536
	global_load_dwordx2 v[46:47], v62, s[0:1]
	global_load_dwordx2 v[48:49], v62, s[0:1] offset:512
	global_load_dwordx2 v[50:51], v62, s[0:1] offset:1024
	global_load_dwordx2 v[54:55], v62, s[0:1] offset:1536
	s_lshl_b32 s0, s12, 9
	s_add_i32 s0, s0, 0
	s_lshl_b32 s1, s12, 11
	v_readlane_b32 s16, v254, 17
	v_lshl_add_u32 v64, v45, 2, s0
	v_mul_u32_u24_e32 v65, 0x1010, v44
	s_add_i32 s1, s16, s1
	v_lshlrev_b32_e32 v45, 9, v45
	v_lshlrev_b32_e32 v44, 2, v44
	v_add3_u32 v140, s1, v45, v44
	v_lshlrev_b32_e32 v45, 2, v168
	v_readlane_b32 s1, v254, 18
	v_ashrrev_i32_e32 v143, 5, v168
	v_lshlrev_b32_e32 v60, 4, v143
	v_add_u32_e32 v142, s1, v45
	v_readlane_b32 s1, v254, 19
	s_mulk_i32 s12, 0x1e20
	v_and_b32_e32 v44, 31, v168
	v_add_u32_e32 v144, s1, v60
	v_readlane_b32 s1, v249, 48
	s_cmp_lg_u32 s1, 0
	v_add_u32_e32 v141, s16, v45
	s_cselect_b64 s[16:17], -1, 0
	s_add_i32 s0, s0, s12
	s_or_b32 s27, s15, 1
	v_lshlrev_b32_e32 v58, 2, v44
	v_readlane_b32 s22, v249, 1
	s_add_i32 s1, 0, 0x14900
	v_add_u32_e32 v148, s0, v39
	s_mul_i32 s0, s27, 0x1010
	v_mov_b32_e32 v59, v33
	v_readlane_b32 s23, v249, 2
	v_add_u32_e32 v145, s1, v58
	v_readlane_b32 s1, v254, 20
	s_add_i32 s0, s0, 0
	v_lshlrev_b32_e32 v32, 2, v248
	v_lshl_add_u64 v[52:53], s[22:23], 0, v[58:59]
	global_load_dword v214, v[52:53], off
	v_readlane_b32 s22, v254, 49
	v_add_u32_e32 v147, s1, v60
	v_add_u32_e32 v149, s0, v39
	v_readlane_b32 s0, v251, 48
	v_mov_b32_e32 v63, v33
	v_readlane_b32 s23, v254, 50
	v_readlane_b32 s1, v251, 49
	v_lshl_add_u64 v[60:61], s[6:7], 0, v[32:33]
	v_and_b32_e32 v32, 0xffffff80, v45
	s_mov_b32 s26, 0
	v_lshl_add_u64 v[56:57], s[22:23], 0, v[58:59]
	v_lshlrev_b32_e32 v146, 16, v44
	v_mov_b32_e32 v39, v44
	v_lshl_add_u64 v[58:59], s[0:1], 0, v[62:63]
	v_lshl_add_u64 v[62:63], s[20:21], 0, v[62:63]
	v_add_u32_e32 v150, 0, v32
	v_add_u32_e32 v151, v64, v65
	v_readlane_b32 s50, v251, 12
	s_branch .LBB0_123

; __device__ __forceinline__ void ln1_router_phase(const Args& a, int l, LAS unsigned char* lds, const int tid, const int rpt) {
;     ...
;         { f32x4 acc0 = {0.f, 0.f, 0.f, 0.f}, acc1 = {0.f, 0.f, 0.f, 0.f};
; #pragma unroll
;           for (int ks = 0; ks < 32; ++ks) { const float av = X[r16 * 1028 + kb + 4 * ks + kq];
;               acc0 = __builtin_amdgcn_mfma_f32_16x16x4f32(av, w0[ks], acc0, 0, 0, 0); acc1 = __builtin_amdgcn_mfma_f32_16x16x4f32(av, w1[ks], acc1, 0, 0, 0); }
; #pragma unroll
;           for (int j = 0; j < 4; ++j) { PART[wave * 512 + (4 * kq + j) * 32 + r16] = acc0[j]; PART[wave * 512 + (4 * kq + j) * 32 + 16 + r16] = acc1[j]; } }
;         __syncthreads();
;         { float s = rb[tid & 31];
; #pragma unroll
;           for (int w = 0; w < 8; ++w) s += PART[w * 512 + tid];
;           LG[tid] = s; }
;         __syncthreads();
;         { const int t = tid >> 5, e = tid & 31; const float v = LG[tid]; int rank = 0;
.LBB0_125:
	s_mov_b32 s12, 1
	s_mov_b32 s22, 0
	s_mov_b32 s23, 0
	ds_read2_b32 v[72:73], v151 offset1:4
	ds_read2_b32 v[164:165], v151 offset0:8 offset1:12
	s_waitcnt lgkmcnt(1)
	v_mfma_f32_16x16x4_f32 v[64:67], v72, v76, 0
	v_mfma_f32_16x16x4_f32 v[68:71], v72, v77, 0
	v_mfma_f32_16x16x4_f32 v[64:67], v73, v78, v[64:67]
	v_mfma_f32_16x16x4_f32 v[68:71], v73, v79, v[68:71]
	ds_read2_b32 v[72:73], v151 offset0:16 offset1:20
	s_waitcnt lgkmcnt(1)
	v_mfma_f32_16x16x4_f32 v[64:67], v164, v80, v[64:67]
	v_mfma_f32_16x16x4_f32 v[68:71], v164, v81, v[68:71]
	v_mfma_f32_16x16x4_f32 v[64:67], v165, v82, v[64:67]
	v_mfma_f32_16x16x4_f32 v[68:71], v165, v83, v[68:71]
	ds_read2_b32 v[164:165], v151 offset0:24 offset1:28
	s_waitcnt lgkmcnt(1)
	v_mfma_f32_16x16x4_f32 v[64:67], v72, v84, v[64:67]
	v_mfma_f32_16x16x4_f32 v[68:71], v72, v85, v[68:71]
	v_mfma_f32_16x16x4_f32 v[64:67], v73, v86, v[64:67]
	v_mfma_f32_16x16x4_f32 v[68:71], v73, v87, v[68:71]
	ds_read2_b32 v[72:73], v151 offset0:32 offset1:36
	s_waitcnt lgkmcnt(1)
	v_mfma_f32_16x16x4_f32 v[64:67], v164, v88, v[64:67]
	v_mfma_f32_16x16x4_f32 v[68:71], v164, v89, v[68:71]
	v_mfma_f32_16x16x4_f32 v[64:67], v165, v90, v[64:67]
	v_mfma_f32_16x16x4_f32 v[68:71], v165, v91, v[68:71]
	ds_read2_b32 v[164:165], v151 offset0:40 offset1:44
	s_waitcnt lgkmcnt(1)
	v_mfma_f32_16x16x4_f32 v[64:67], v72, v100, v[64:67]
	v_mfma_f32_16x16x4_f32 v[68:71], v72, v92, v[68:71]
	v_mfma_f32_16x16x4_f32 v[64:67], v73, v93, v[64:67]
	v_mfma_f32_16x16x4_f32 v[68:71], v73, v94, v[68:71]
	ds_read2_b32 v[72:73], v151 offset0:48 offset1:52
	s_waitcnt lgkmcnt(1)
	v_mfma_f32_16x16x4_f32 v[64:67], v164, v95, v[64:67]
	v_mfma_f32_16x16x4_f32 v[68:71], v164, v96, v[68:71]
	v_mfma_f32_16x16x4_f32 v[64:67], v165, v97, v[64:67]
	v_mfma_f32_16x16x4_f32 v[68:71], v165, v98, v[68:71]
	ds_read2_b32 v[164:165], v151 offset0:56 offset1:60
	s_waitcnt lgkmcnt(1)
	v_mfma_f32_16x16x4_f32 v[64:67], v72, v99, v[64:67]
	v_mfma_f32_16x16x4_f32 v[68:71], v72, v117, v[68:71]
	v_mfma_f32_16x16x4_f32 v[64:67], v73, v118, v[64:67]
	v_mfma_f32_16x16x4_f32 v[68:71], v73, v119, v[68:71]
	ds_read2_b32 v[72:73], v151 offset0:64 offset1:68
	s_waitcnt lgkmcnt(1)
	v_mfma_f32_16x16x4_f32 v[64:67], v164, v120, v[64:67]
	v_mfma_f32_16x16x4_f32 v[68:71], v164, v121, v[68:71]
	v_mfma_f32_16x16x4_f32 v[64:67], v165, v122, v[64:67]
	v_mfma_f32_16x16x4_f32 v[68:71], v165, v123, v[68:71]
	ds_read2_b32 v[164:165], v151 offset0:72 offset1:76
	s_waitcnt lgkmcnt(1)
	v_mfma_f32_16x16x4_f32 v[64:67], v72, v101, v[64:67]
	v_mfma_f32_16x16x4_f32 v[68:71], v72, v102, v[68:71]
	v_mfma_f32_16x16x4_f32 v[64:67], v73, v103, v[64:67]
	v_mfma_f32_16x16x4_f32 v[68:71], v73, v104, v[68:71]
	ds_read2_b32 v[72:73], v151 offset0:80 offset1:84
	s_waitcnt lgkmcnt(1)
	v_mfma_f32_16x16x4_f32 v[64:67], v164, v105, v[64:67]
	v_mfma_f32_16x16x4_f32 v[68:71], v164, v106, v[68:71]
	v_mfma_f32_16x16x4_f32 v[64:67], v165, v107, v[64:67]
	v_mfma_f32_16x16x4_f32 v[68:71], v165, v108, v[68:71]
	ds_read2_b32 v[164:165], v151 offset0:88 offset1:92
	s_waitcnt lgkmcnt(1)
	v_mfma_f32_16x16x4_f32 v[64:67], v72, v109, v[64:67]
	v_mfma_f32_16x16x4_f32 v[68:71], v72, v110, v[68:71]
	v_mfma_f32_16x16x4_f32 v[64:67], v73, v111, v[64:67]
	v_mfma_f32_16x16x4_f32 v[68:71], v73, v112, v[68:71]
	ds_read2_b32 v[72:73], v151 offset0:96 offset1:100
	s_waitcnt lgkmcnt(1)
	v_mfma_f32_16x16x4_f32 v[64:67], v164, v113, v[64:67]
	v_mfma_f32_16x16x4_f32 v[68:71], v164, v114, v[68:71]
	v_mfma_f32_16x16x4_f32 v[64:67], v165, v115, v[64:67]
	v_mfma_f32_16x16x4_f32 v[68:71], v165, v116, v[68:71]
	ds_read2_b32 v[164:165], v151 offset0:104 offset1:108
	s_waitcnt lgkmcnt(1)
	v_mfma_f32_16x16x4_f32 v[64:67], v72, v124, v[64:67]
	v_mfma_f32_16x16x4_f32 v[68:71], v72, v125, v[68:71]
	v_mfma_f32_16x16x4_f32 v[64:67], v73, v126, v[64:67]
	v_mfma_f32_16x16x4_f32 v[68:71], v73, v127, v[68:71]
	ds_read2_b32 v[72:73], v151 offset0:112 offset1:116
	s_waitcnt lgkmcnt(1)
	v_mfma_f32_16x16x4_f32 v[64:67], v164, v128, v[64:67]
	v_mfma_f32_16x16x4_f32 v[68:71], v164, v129, v[68:71]
	v_mfma_f32_16x16x4_f32 v[64:67], v165, v130, v[64:67]
	v_mfma_f32_16x16x4_f32 v[68:71], v165, v131, v[68:71]
	ds_read2_b32 v[164:165], v151 offset0:120 offset1:124
	s_waitcnt lgkmcnt(1)
	v_mfma_f32_16x16x4_f32 v[64:67], v72, v132, v[64:67]
	v_mfma_f32_16x16x4_f32 v[68:71], v72, v133, v[68:71]
	v_mfma_f32_16x16x4_f32 v[64:67], v73, v134, v[64:67]
	v_mfma_f32_16x16x4_f32 v[68:71], v73, v135, v[68:71]
	s_waitcnt lgkmcnt(0)
	v_mfma_f32_16x16x4_f32 v[64:67], v164, v136, v[64:67]
	v_mfma_f32_16x16x4_f32 v[68:71], v164, v137, v[68:71]
	v_mfma_f32_16x16x4_f32 v[64:67], v165, v138, v[64:67]
	v_mfma_f32_16x16x4_f32 v[68:71], v165, v139, v[68:71]
	s_nop 9
	ds_write2_b32 v140, v64, v68 offset1:16
	ds_write2_b32 v140, v65, v69 offset0:32 offset1:48
	ds_write2_b32 v140, v66, v70 offset0:64 offset1:80
	ds_write2_b32 v140, v67, v71 offset0:96 offset1:112
	s_waitcnt lgkmcnt(0)
	s_barrier
	v_mov_b32_e32 v32, v214
	ds_read2st64_b32 v[64:65], v141 offset1:8
	ds_read2st64_b32 v[66:67], v141 offset0:16 offset1:24
	ds_read2st64_b32 v[68:69], v141 offset0:32 offset1:40
	s_waitcnt lgkmcnt(2)
	v_add_f32_e32 v32, v32, v64
	v_add_f32_e32 v32, v32, v65
	ds_read2st64_b32 v[64:65], v141 offset0:48 offset1:56
	s_waitcnt lgkmcnt(2)
	v_add_f32_e32 v32, v32, v66
	v_add_f32_e32 v32, v32, v67
	s_waitcnt lgkmcnt(1)
	v_add_f32_e32 v32, v32, v68
	v_add_f32_e32 v32, v32, v69
	s_waitcnt lgkmcnt(0)
	v_add_f32_e32 v32, v32, v64
	v_add_f32_e32 v32, v32, v65
	ds_write_b32 v142, v32
	s_waitcnt lgkmcnt(0)
	ds_read_b32 v32, v142
	v_mov_b32_e32 v65, 0
	v_mov_b32_e32 v64, 0
	s_waitcnt lgkmcnt(0)
	v_mov_b32_e32 v45, v32
